# FoX prompt QK^T stage: per-MFMA-pair counted LDS waits and the 8 forget-bias LDS reads issued in the MFMA shadow after MFMA 10 (on top of v23)
# speedup vs baseline: 1.0104x; 1.0029x over previous
.LBB0_720:
	s_lshl_b32 s37, s89, 14
	v_add_u32_e32 v2, s37, v137
	v_add_u32_e32 v3, v2, v146
	ds_read_b128 v[70:73], v3
	ds_read_b128 v[74:77], v3 offset:8192
	v_add_u32_e32 v3, v2, v147
	ds_read_b128 v[160:163], v3
	ds_read_b128 v[164:167], v3 offset:8192
	v_add_u32_e32 v3, v2, v148
	ds_read_b128 v[168:171], v3
	ds_read_b128 v[172:175], v3 offset:8192
	v_add_u32_e32 v3, v2, v149
	ds_read_b128 v[176:179], v3
	ds_read_b128 v[180:183], v3 offset:8192
	v_add_u32_e32 v3, v2, v150
	ds_read_b128 v[184:187], v3
	ds_read_b128 v[188:191], v3 offset:8192
	v_add_u32_e32 v3, v2, v151
	ds_read_b128 v[192:195], v3
	ds_read_b128 v[196:199], v3 offset:8192
	v_add_u32_e32 v3, v2, v152
	v_add_u32_e32 v2, v2, v153
	ds_read_b128 v[200:203], v3
	ds_read_b128 v[204:207], v3 offset:8192
	ds_read_b128 v[208:211], v2
	ds_read_b128 v[216:219], v2 offset:8192
	s_waitcnt lgkmcnt(14)
	v_mfma_f32_32x32x16_bf16 v[86:101], v[70:73], v[102:105], 0
	v_mfma_f32_32x32x16_bf16 v[70:85], v[74:77], v[102:105], 0
	s_waitcnt lgkmcnt(12)
	v_mfma_f32_32x32x16_bf16 v[86:101], v[160:163], v[106:109], v[86:101]
	v_mfma_f32_32x32x16_bf16 v[70:85], v[164:167], v[106:109], v[70:85]
	s_waitcnt lgkmcnt(10)
	v_mfma_f32_32x32x16_bf16 v[86:101], v[168:171], v[110:113], v[86:101]
	v_mfma_f32_32x32x16_bf16 v[70:85], v[172:175], v[110:113], v[70:85]
	s_waitcnt lgkmcnt(8)
	v_mfma_f32_32x32x16_bf16 v[86:101], v[176:179], v[114:117], v[86:101]
	v_mfma_f32_32x32x16_bf16 v[70:85], v[180:183], v[114:117], v[70:85]
	s_waitcnt lgkmcnt(6)
	v_mfma_f32_32x32x16_bf16 v[86:101], v[184:187], v[118:121], v[86:101]
	v_mfma_f32_32x32x16_bf16 v[70:85], v[188:191], v[118:121], v[70:85]
	v_add_u32_e32 v2, s70, v155
	v_add_u32_e32 v3, 0x1e000, v2
	v_add_u32_e32 v5, 0x1e080, v2
	ds_read_b128 v[160:163], v3
	ds_read_b128 v[164:167], v5
	v_add_u32_e32 v3, 0x1e020, v2
	v_add_u32_e32 v5, 0x1e0a0, v2
	ds_read_b128 v[168:171], v3
	ds_read_b128 v[172:175], v5
	v_add_u32_e32 v3, 0x1e040, v2
	v_add_u32_e32 v5, 0x1e0c0, v2
	ds_read_b128 v[176:179], v3
	ds_read_b128 v[180:183], v5
	v_add_u32_e32 v3, 0x1e060, v2
	v_add_u32_e32 v2, 0x1e0e0, v2
	ds_read_b128 v[184:187], v3
	ds_read_b128 v[188:191], v2
	s_waitcnt lgkmcnt(12)
	v_mfma_f32_32x32x16_bf16 v[86:101], v[192:195], v[122:125], v[86:101]
	v_mfma_f32_32x32x16_bf16 v[70:85], v[196:199], v[122:125], v[70:85]
	s_waitcnt lgkmcnt(10)
	v_mfma_f32_32x32x16_bf16 v[86:101], v[200:203], v[126:129], v[86:101]
	v_mfma_f32_32x32x16_bf16 v[70:85], v[204:207], v[126:129], v[70:85]
	s_waitcnt lgkmcnt(8)
	v_mfma_f32_32x32x16_bf16 v[86:101], v[208:211], v[130:133], v[86:101]
	v_mfma_f32_32x32x16_bf16 v[70:85], v[216:219], v[130:133], v[70:85]
	s_waitcnt lgkmcnt(0)
	s_nop 12
	v_fma_f32 v2, v100, s86, -v186
	v_fma_f32 v3, v101, s86, -v187
	v_fma_f32 v88, v88, s86, -v162
	v_fma_f32 v89, v89, s86, -v163
	v_fma_f32 v86, v86, s86, -v160
	v_fma_f32 v87, v87, s86, -v161
	v_fma_f32 v98, v98, s86, -v184
	v_fma_f32 v99, v99, s86, -v185
	v_fma_f32 v96, v96, s86, -v178
	v_fma_f32 v97, v97, s86, -v179
	v_fma_f32 v94, v94, s86, -v176
	v_fma_f32 v95, v95, s86, -v177
	v_fma_f32 v92, v92, s86, -v170
	v_fma_f32 v93, v93, s86, -v171
	v_fma_f32 v90, v90, s86, -v168
	v_fma_f32 v91, v91, s86, -v169
	v_fma_f32 v84, v84, s86, -v190
	v_fma_f32 v85, v85, s86, -v191
	v_fma_f32 v82, v82, s86, -v188
	v_fma_f32 v83, v83, s86, -v189
	v_fma_f32 v80, v80, s86, -v182
	v_fma_f32 v81, v81, s86, -v183
	v_fma_f32 v78, v78, s86, -v180
	v_fma_f32 v79, v79, s86, -v181
	v_fma_f32 v76, v76, s86, -v174
	v_fma_f32 v77, v77, s86, -v175
	v_fma_f32 v74, v74, s86, -v172
	v_fma_f32 v75, v75, s86, -v173
	v_fma_f32 v72, v72, s86, -v166
	v_fma_f32 v73, v73, s86, -v167
	s_cmp_le_i32 s85, s95
	v_fma_f32 v70, v70, s86, -v164
	v_fma_f32 v71, v71, s86, -v165
	s_cbranch_scc1 .LBB0_722
	v_cmp_gt_i32_e64 s[66:67], 26, v156
	v_cmp_gt_i32_e64 s[68:69], 27, v156
	v_cmp_gt_i32_e64 s[64:65], 25, v156
	s_and_b64 s[66:67], s[68:69], s[66:67]
	v_cmp_gt_i32_e64 s[62:63], 24, v156
	s_and_b64 s[64:65], s[66:67], s[64:65]
	v_cmp_gt_i32_e64 s[60:61], 19, v156
	s_and_b64 s[62:63], s[64:65], s[62:63]
	v_cmp_gt_i32_e64 s[58:59], 18, v156
	s_and_b64 s[60:61], s[62:63], s[60:61]
	v_cmp_gt_i32_e64 s[56:57], 17, v156
	s_and_b64 s[58:59], s[60:61], s[58:59]
	v_cmp_gt_i32_e64 s[54:55], 16, v156
	s_and_b64 s[56:57], s[58:59], s[56:57]
	v_cmp_gt_i32_e64 s[52:53], 11, v156
	s_and_b64 s[54:55], s[56:57], s[54:55]
	v_cmp_gt_i32_e64 s[50:51], 10, v156
	s_and_b64 s[52:53], s[54:55], s[52:53]
	v_cmp_gt_i32_e64 s[48:49], 9, v156
	s_and_b64 s[50:51], s[52:53], s[50:51]
	v_cmp_gt_i32_e64 s[46:47], 8, v156
	s_and_b64 s[48:49], s[50:51], s[48:49]
	v_cmp_gt_i32_e64 s[44:45], 3, v156
	s_and_b64 s[46:47], s[48:49], s[46:47]
	v_cmp_gt_i32_e64 s[42:43], 2, v156
	s_and_b64 s[44:45], s[46:47], s[44:45]
	v_cmp_gt_i32_e64 s[40:41], 1, v156
	s_and_b64 s[42:43], s[44:45], s[42:43]
	v_cmp_gt_i32_e64 s[0:1], 0, v156
	s_and_b64 s[40:41], s[42:43], s[40:41]
	s_and_b64 s[0:1], s[40:41], s[0:1]
	v_cmp_gt_i32_e64 s[34:35], 58, v156
	v_cndmask_b32_e64 v86, v86, v247, s[0:1]
	v_cmp_gt_i32_e64 s[0:1], 59, v156
	v_cmp_gt_i32_e64 s[30:31], 57, v156
	v_cmp_gt_i32_e64 s[28:29], 56, v156
	v_cndmask_b32_e64 v85, v85, v247, s[0:1]
	s_and_b64 s[0:1], s[0:1], s[34:35]
	v_cndmask_b32_e64 v84, v84, v247, s[0:1]
	s_and_b64 s[0:1], s[0:1], s[30:31]
	v_cmp_gt_i32_e64 s[26:27], 51, v156
	v_cndmask_b32_e64 v83, v83, v247, s[0:1]
	s_and_b64 s[0:1], s[0:1], s[28:29]
	v_cmp_gt_i32_e64 s[24:25], 50, v156
	v_cndmask_b32_e64 v82, v82, v247, s[0:1]
	s_and_b64 s[0:1], s[0:1], s[26:27]
	v_cmp_gt_i32_e64 s[22:23], 49, v156
	v_cndmask_b32_e64 v81, v81, v247, s[0:1]
	s_and_b64 s[0:1], s[0:1], s[24:25]
	v_cmp_gt_i32_e64 s[20:21], 48, v156
	v_cndmask_b32_e64 v80, v80, v247, s[0:1]
	s_and_b64 s[0:1], s[0:1], s[22:23]
	v_cmp_gt_i32_e64 s[18:19], 43, v156
	v_cndmask_b32_e64 v79, v79, v247, s[0:1]
	s_and_b64 s[0:1], s[0:1], s[20:21]
	v_cmp_gt_i32_e64 s[16:17], 42, v156
	v_cndmask_b32_e64 v78, v78, v247, s[0:1]
	s_and_b64 s[0:1], s[0:1], s[18:19]
	v_cmp_gt_i32_e64 s[14:15], 41, v156
	v_cndmask_b32_e64 v77, v77, v247, s[0:1]
	s_and_b64 s[0:1], s[0:1], s[16:17]
	v_cmp_gt_i32_e64 s[12:13], 40, v156
	v_cndmask_b32_e64 v76, v76, v247, s[0:1]
	s_and_b64 s[0:1], s[0:1], s[14:15]
	v_cmp_gt_i32_e64 s[10:11], 35, v156
	v_cndmask_b32_e64 v75, v75, v247, s[0:1]
	s_and_b64 s[0:1], s[0:1], s[12:13]
	v_cmp_gt_i32_e64 s[8:9], 34, v156
	v_cndmask_b32_e64 v74, v74, v247, s[0:1]
	s_and_b64 s[0:1], s[0:1], s[10:11]
	v_cmp_gt_i32_e64 s[6:7], 33, v156
	v_cndmask_b32_e64 v73, v73, v247, s[0:1]
	s_and_b64 s[0:1], s[0:1], s[8:9]
	v_cmp_gt_i32_e32 vcc, 32, v156
	v_cndmask_b32_e64 v72, v72, v247, s[0:1]
	s_and_b64 s[0:1], s[0:1], s[6:7]
	s_and_b64 vcc, s[0:1], vcc
	v_cndmask_b32_e64 v3, v3, v247, s[68:69]
	v_cndmask_b32_e64 v2, v2, v247, s[66:67]
	v_cndmask_b32_e64 v99, v99, v247, s[64:65]
	v_cndmask_b32_e64 v98, v98, v247, s[62:63]
	v_cndmask_b32_e64 v97, v97, v247, s[60:61]
	v_cndmask_b32_e64 v96, v96, v247, s[58:59]
	v_cndmask_b32_e64 v95, v95, v247, s[56:57]
	v_cndmask_b32_e64 v94, v94, v247, s[54:55]
	v_cndmask_b32_e64 v93, v93, v247, s[52:53]
	v_cndmask_b32_e64 v92, v92, v247, s[50:51]
	s_mov_b32 s51, 0x40c000
	v_cndmask_b32_e64 v91, v91, v247, s[48:49]
	s_mov_b64 s[48:49], 0x7ffff
	v_cndmask_b32_e64 v90, v90, v247, s[46:47]
	s_mov_b32 s47, 0x120000
	v_cndmask_b32_e64 v89, v89, v247, s[44:45]
	v_cndmask_b32_e64 v88, v88, v247, s[42:43]
	v_cndmask_b32_e64 v87, v87, v247, s[40:41]
	s_mov_b32 s40, 0x41000000
	v_cndmask_b32_e64 v71, v71, v247, s[0:1]
	v_cndmask_b32_e32 v70, v70, v247, vcc
